# P6 de-phasing: the 106 workgroups that own five tiles (one tile of slack) start 15 us later
# speedup vs baseline: 1.0076x; 1.0076x over previous
.LBB0_2350:
	s_or_b64 exec, exec, s[0:1]
	s_add_u32 s4, s90, 0xa06ea00
	s_addc_u32 s5, s91, 0
	s_add_u32 s97, s90, 0x800000
	s_addc_u32 s2, s91, 0
	v_mov_b32_e32 v2, v0
	s_cmpk_gt_i32 s96, 0x595
	s_waitcnt lgkmcnt(0)
	s_barrier
	s_cbranch_scc1 .LBB0_2467
	s_cmpk_lt_u32 s96, 0x96
	s_cbranch_scc1 .Lstg6_done
	s_sleep 127
	s_sleep 127
	s_sleep 127
	s_sleep 127
	s_sleep 60
.Lstg6_done:
	v_lshlrev_b32_e32 v182, 4, v2
	v_add_u32_e32 v4, 0x2000, v182
	v_ashrrev_i32_e32 v5, 31, v4
	v_lshrrev_b32_e32 v5, 22, v5
	v_add_u32_e32 v5, v4, v5
	v_ashrrev_i32_e32 v5, 10, v5
	v_mul_i32_i24_e32 v7, 0x400, v5
	v_sub_u32_e32 v4, v4, v7
	v_lshrrev_b32_e32 v7, 4, v4
	v_bitop3_b32 v4, v7, v4, 32 bitop3:0x6c
	v_ashrrev_i32_e32 v7, 31, v4
	v_bfe_i32 v11, v2, 27, 1
	v_lshrrev_b32_e32 v7, 26, v7
	v_lshrrev_b32_e32 v11, 22, v11
	v_add_u32_e32 v7, v4, v7
	v_add_u32_e32 v11, v182, v11
	v_ashrrev_i32_e32 v8, 6, v7
	v_and_b32_e32 v7, 0xc0, v7
	v_and_b32_e32 v11, 0xfffffc00, v11
	v_sub_u32_e32 v4, v4, v7
	v_mov_b32_e32 v7, 1
	v_sub_u32_e32 v11, v182, v11
	v_lshlrev_b32_e32 v6, 5, v5
	v_ashrrev_i16_sdwa v4, v7, sext(v4) dst_sel:DWORD dst_unused:UNUSED_PAD src0_sel:DWORD src1_sel:BYTE_0
	v_lshlrev_b32_e32 v9, 3, v5
	v_lshrrev_b32_e32 v12, 4, v11
	v_and_b32_e32 v6, 32, v6
	v_bfe_i32 v4, v4, 0, 16
	v_and_b32_e32 v9, 0x1ffff0, v9
	v_bitop3_b32 v11, v12, v11, 32 bitop3:0x6c
	v_add_u32_e32 v6, v6, v4
	v_add_lshl_u32 v9, v8, v9, 11
	v_ashrrev_i32_e32 v12, 31, v11
	v_lshl_add_u32 v162, v6, 1, v9
	v_ashrrev_i32_e32 v6, 31, v2
	v_lshrrev_b32_e32 v12, 26, v12
	v_lshrrev_b32_e32 v6, 26, v6
	v_add_u32_e32 v12, v11, v12
	v_add_u32_e32 v6, v2, v6
	v_ashrrev_i32_e32 v13, 6, v12
	v_and_b32_e32 v12, 0xc0, v12
	v_ashrrev_i32_e32 v9, 6, v6
	v_sub_u32_e32 v11, v11, v12
	v_lshlrev_b32_e32 v10, 5, v9
	v_ashrrev_i16_sdwa v7, v7, sext(v11) dst_sel:DWORD dst_unused:UNUSED_PAD src0_sel:DWORD src1_sel:BYTE_0
	v_lshlrev_b32_e32 v11, 3, v9
	v_lshlrev_b32_e32 v9, 14, v9
	v_and_b32_e32 v9, 0xffff8000, v9
	v_and_b32_e32 v10, 32, v10
	v_bfe_i32 v7, v7, 0, 16
	v_and_b32_e32 v11, 0x1ffff0, v11
	v_lshl_add_u32 v9, v13, 11, v9
	v_add_u32_e32 v10, v10, v7
	v_add_lshl_u32 v11, v13, v11, 11
	s_movk_i32 s74, 0x100
	v_and_or_b32 v6, v6, 64, v9
	v_and_b32_e32 v3, 15, v2
	v_lshl_add_u32 v164, v10, 1, v11
	v_and_b32_e32 v10, 48, v2
	v_ashrrev_i32_e32 v11, 8, v2
	v_lshlrev_b32_e32 v12, 2, v2
	s_add_i32 s38, 16, 0x10000
	s_add_i32 s39, 16, 0x14000
	s_add_i32 s72, 16, 0x18000
	s_add_i32 s73, 16, 0x1c000
	v_cmp_gt_u32_e64 s[6:7], s74, v2
	v_lshlrev_b32_e32 v2, 6, v2
	s_movk_i32 s8, 0x3c0
	v_lshl_add_u32 v168, v7, 1, v6
	v_lshlrev_b32_e32 v6, 14, v5
	v_lshlrev_b32_e32 v3, 6, v3
	v_and_b32_e32 v12, 32, v12
	v_and_b32_e32 v18, 0x3000, v2
	v_and_or_b32 v2, v2, s8, v10
	s_add_u32 s8, s88, 0x874e000
	v_and_b32_e32 v6, 0xffff8000, v6
	v_cmp_eq_u32_e64 s[0:1], 1, v11
	v_bitop3_b32 v3, v3, v12, v10 bitop3:0x36
	v_lshlrev_b32_e32 v11, 13, v11
	s_addc_u32 s9, s89, 0
	v_lshl_add_u32 v6, v8, 11, v6
	v_lshlrev_b32_e32 v5, 6, v5
	v_mov_b32_e32 v167, 0
	v_add_u32_e32 v14, s38, v3
	v_add_u32_e32 v15, s39, v3
	v_add_u32_e32 v16, s72, v3
	v_add_u32_e32 v17, s73, v3
	v_add_u32_e32 v3, 16, v3
	v_xad_u32 v2, v2, v12, 16
	v_or_b32_e32 v10, 0x800, v11
	v_or_b32_e32 v12, 0x1000, v11
	v_or_b32_e32 v19, 0x1800, v11
	s_add_u32 s14, s88, 0x8206000
	v_and_or_b32 v5, v5, 64, v6
	v_add_u32_e32 v183, 16, v182
	v_add_u32_e32 v188, s38, v182
	v_add_u32_e32 v190, s39, v182
	v_mov_b32_e32 v165, v167
	v_mov_b32_e32 v163, v167
	s_addc_u32 s15, s89, 0
	v_mov_b32_e32 v169, v167
	v_lshl_add_u32 v170, v4, 1, v5
	v_mov_b32_e32 v171, v167
	v_add_u32_e32 v184, 0x2000, v183
	v_add_u32_e32 v185, 0x4000, v183
	v_add_u32_e32 v186, 0x6000, v183
	s_mov_b64 s[16:17], 0x80
	s_mov_b64 s[18:19], 0x1eaea80
	s_mov_b64 s[20:21], 0x800100
	s_mov_b64 s[22:23], 0x1e6eb00
	s_mov_b64 s[24:25], 0x840100
	s_mov_b64 s[26:27], 0x1eaeb00
	s_mov_b64 s[28:29], 0x800180
	s_mov_b64 s[30:31], 0x1e6eb80
	s_mov_b64 s[34:35], 0x840180
	s_mov_b64 s[36:37], 0x780
	s_movk_i32 s75, 0x3fff
	s_movk_i32 s76, 0x5800
	v_mov_b32_e32 v187, 0x358637bd
	s_mov_b32 s77, 0x800000
	s_movk_i32 s78, 0x210
	s_movk_i32 s79, 0x1ffd
	s_movk_i32 s80, 0xe002
	s_movk_i32 s81, 0x2c00
	s_movk_i32 s82, 0x2100
	s_movk_i32 s83, 0x1600
	v_add_u32_e32 v189, 0x2000, v188
	v_add_u32_e32 v191, 0x2000, v190
	v_add_u32_e32 v192, v14, v18
	v_add_u32_e32 v193, v3, v11
	v_add_u32_e32 v194, v2, v10
	v_add_u32_e32 v195, v2, v12
	v_add_u32_e32 v196, v2, v19
	v_add_u32_e32 v197, v15, v18
	v_add_u32_e32 v199, v16, v18
	v_add_u32_e32 v200, v17, v18
	s_mov_b32 s84, s96
